# DeltaNet step D: output-store addresses from a running 64-bit base (+/-4096 per row via SGPR stride) instead of 6 VALU per store; dead row-index constants removed
# baseline (speedup 1.0000x reference)
.LBB0_705:
	v_mov_b32_e32 v0, s60
	v_cndmask_b32_e64 v155, v111, v0, s[6:7]
	s_add_i32 s18, 16, 0x21000
	s_add_i32 s19, 16, 0x8800
	v_mov_b32_e32 v3, v120
	v_mov_b32_e32 v0, v107
	v_mov_b32_e32 v74, v121
	s_and_b64 s[0:1], s[14:15], exec
	s_waitcnt lgkmcnt(0)
	s_barrier
	s_cselect_b32 s0, s19, s18
	v_mul_lo_u32 v0, v3, s24
	s_add_i32 s1, 16, 0x16400
	v_lshlrev_b32_e32 v68, 3, v74
	v_add3_u32 v0, s1, v0, v68
	v_add_u32_e32 v1, 0x1000, v0
	v_mul_lo_u32 v69, v3, 40
	v_lshl_add_u32 v3, v3, 1, s43
	v_mul_lo_u32 v74, v74, s25
	ds_read_b64 v[64:65], v1 offset:512
	ds_read_b64 v[66:67], v1 offset:544
	v_add_u32_e32 v1, 0x1800, v0
	v_add3_u32 v68, s40, v68, v69
	v_add_u32_e32 v156, v3, v74
	ds_read_b64 v[72:73], v0 offset:2304
	ds_read_b64 v[60:61], v1 offset:768
	ds_read_b64 v[62:63], v1 offset:800
	ds_read_b64 v[0:1], v0 offset:6976
	ds_read_b64 v[84:85], v68
	ds_read_b64 v[86:87], v68 offset:640
	ds_read_b64 v[70:71], v68 offset:1920
	ds_read_b64 v[68:69], v68 offset:1280
	ds_read_u16 v188, v156 offset:61696
	v_add_u32_e32 v75, 0xd000, v3
	v_add_u32_e32 v101, 0x6510, v74
	v_add_u32_e32 v162, v75, v101
	ds_read_u16 v77, v162
	ds_read_u16 v189, v156 offset:62224
	v_add_u32_e32 v102, 0x6720, v74
	v_add_u32_e32 v163, v75, v102
	ds_read_u16 v78, v163
	v_add_u32_e32 v100, 0x6300, v74
	ds_read_u16 v190, v156 offset:62752
	v_add_u32_e32 v96, 0x4200, v74
	v_add_u32_e32 v97, 0x4410, v74
	v_add_u32_e32 v98, 0x4620, v74
	v_add_u32_e32 v99, 0x4830, v74
	v_add_u32_e32 v74, 0x6930, v74
	v_add_u32_e32 v164, v75, v74
	v_add_u32_e32 v157, v75, v96
	v_add_u32_e32 v158, v75, v97
	v_add_u32_e32 v159, v75, v98
	v_add_u32_e32 v160, v75, v99
	v_add_u32_e32 v161, v75, v100
	ds_read_u16 v192, v164
	ds_read_u16 v191, v156 offset:63280
	v_add_u32_e32 v75, 0xd020, v3
	ds_read_u16 v193, v157
	v_add_u32_e32 v181, v75, v97
	v_add_u32_e32 v185, v75, v101
	v_add_u32_e32 v182, v75, v98
	v_add_u32_e32 v186, v75, v102
	ds_read_u16 v194, v158
	v_add_u32_e32 v180, v75, v96
	v_add_u32_e32 v183, v75, v99
	v_add_u32_e32 v184, v75, v100
	v_add_u32_e32 v187, v75, v74
	ds_read_u16 v195, v159
	ds_read_u16 v196, v160
	ds_read_u16 v76, v161
	s_waitcnt lgkmcnt(1)
	v_lshlrev_b32_e32 v88, 16, v188
	v_lshlrev_b32_e32 v89, 16, v189
	v_lshlrev_b32_e32 v90, 16, v190
	v_lshlrev_b32_e32 v77, 16, v77
	v_lshlrev_b32_e32 v78, 16, v78
	v_lshlrev_b32_e32 v79, 16, v192
	v_lshlrev_b32_e32 v91, 16, v191
	v_lshlrev_b32_e32 v80, 16, v193
	v_lshlrev_b32_e32 v81, 16, v194
	v_lshlrev_b32_e32 v82, 16, v195
	v_lshlrev_b32_e32 v83, 16, v196
	ds_read_u16 v168, v156 offset:53248
	ds_read_u16 v3, v156 offset:53280
	ds_read_u16 v92, v156 offset:53808
	ds_read_u16 v93, v156 offset:62256
	ds_read_u16 v97, v181
	ds_read_u16 v101, v185
	ds_read_u16 v94, v156 offset:62784
	ds_read_u16 v98, v182
	ds_read_u16 v102, v186
	s_waitcnt lgkmcnt(6)
	v_lshlrev_b32_e32 v165, 16, v92
	ds_read_u16 v92, v156 offset:54336
	ds_read_u16 v95, v156 offset:63312
	ds_read_u16 v99, v183
	ds_read_u16 v74, v187
	ds_read_u16 v96, v180
	ds_read_u16 v100, v184
	s_waitcnt lgkmcnt(5)
	v_lshlrev_b32_e32 v166, 16, v92
	ds_read_u16 v92, v156 offset:54864
	v_lshlrev_b32_e32 v3, 16, v3
	v_lshlrev_b32_e32 v76, 16, v76
	v_lshlrev_b32_e32 v93, 16, v93
	v_lshlrev_b32_e32 v94, 16, v94
	s_waitcnt lgkmcnt(0)
	v_lshlrev_b32_e32 v167, 16, v92
	ds_read_u16 v92, v156 offset:61728
	ds_read_u16 v169, v156 offset:54832
	ds_read_u16 v170, v156 offset:53776
	ds_read_u16 v171, v156 offset:54304
	v_lshlrev_b32_e32 v95, 16, v95
	v_lshlrev_b32_e32 v96, 16, v96
	v_lshlrev_b32_e32 v97, 16, v97
	s_waitcnt lgkmcnt(3)
	v_lshlrev_b32_e32 v92, 16, v92
	v_lshlrev_b32_e32 v98, 16, v98
	v_lshlrev_b32_e32 v99, 16, v99
	v_lshlrev_b32_e32 v100, 16, v100
	v_lshlrev_b32_e32 v101, 16, v101
	v_lshlrev_b32_e32 v102, 16, v102
	v_lshlrev_b32_e32 v103, 16, v74
	v_mov_b32_e32 v140, v84
	v_mov_b32_e32 v141, v85
	v_mov_b32_e32 v142, v2
	v_mov_b32_e32 v143, v2
	s_waitcnt lgkmcnt(2)
	v_lshlrev_b32_e32 v84, 16, v169
	v_lshlrev_b32_e32 v85, 16, v168
	s_waitcnt lgkmcnt(1)
	v_lshlrev_b32_e32 v168, 16, v170
	s_waitcnt lgkmcnt(0)
	v_lshlrev_b32_e32 v169, 16, v171
	v_cvt_pk_bf16_f32 v169, v169, v84
	v_cvt_pk_bf16_f32 v168, v85, v168
	v_mov_b32_e32 v170, v2
	v_mov_b32_e32 v171, v2
	v_mov_b32_e32 v74, v2
	v_mov_b32_e32 v75, v2
	v_mfma_f32_16x16x32_bf16 v[168:171], v[140:143], v[168:171], 0
	v_cvt_pk_bf16_f32 v173, v166, v167
	v_cvt_pk_bf16_f32 v172, v3, v165
	v_mov_b32_e32 v174, v2
	v_mov_b32_e32 v175, v2
	v_mov_b32_e32 v84, v86
	v_mov_b32_e32 v85, v87
	v_mfma_f32_16x16x32_bf16 v[140:143], v[140:143], v[172:175], 0
	s_nop 0
	v_cvt_pk_bf16_f32 v173, v170, v171
	v_cvt_pk_bf16_f32 v172, v168, v169
	v_mov_b32_e32 v86, v2
	v_mov_b32_e32 v87, v2
	v_mfma_f32_16x16x32_bf16 v[88:91], v[72:75], v[172:175], v[88:91]
	v_mov_b32_e32 v176, v2
	v_mov_b32_e32 v177, v2
	v_mov_b32_e32 v178, v2
	v_mov_b32_e32 v179, v2
	v_mov_b32_e32 v3, v2
	s_nop 2
	v_cvt_pk_bf16_f32 v175, v90, v91
	v_cvt_pk_bf16_f32 v174, v88, v89
	s_cmp_lg_u32 16, -1
	s_cselect_b32 s1, s41, 0
	v_mfma_f32_16x16x32_bf16 v[88:91], v[84:87], v[174:177], 0
	v_cvt_pk_bf16_f32 v177, v142, v143
	v_cvt_pk_bf16_f32 v176, v140, v141
	s_nop 1
	v_mfma_f32_16x16x32_bf16 v[72:75], v[72:75], v[176:179], v[92:95]
	s_nop 2
	v_cvt_pk_bf16_f32 v175, v90, v91
	v_cvt_pk_bf16_f32 v174, v88, v89
	v_mov_b32_e32 v94, v2
	v_mov_b32_e32 v95, v2
	s_nop 0
	v_cvt_pk_bf16_f32 v93, v74, v75
	v_cvt_pk_bf16_f32 v92, v72, v73
	v_mfma_f32_16x16x32_bf16 v[80:83], v[64:67], v[172:175], v[80:83]
	s_nop 0
	v_mfma_f32_16x16x32_bf16 v[72:75], v[84:87], v[92:95], 0
	v_mov_b32_e32 v84, v68
	v_mov_b32_e32 v85, v69
	s_nop 3
	v_cvt_pk_bf16_f32 v93, v82, v83
	v_cvt_pk_bf16_f32 v92, v80, v81
	v_mfma_f32_16x16x32_bf16 v[76:79], v[60:63], v[172:175], v[76:79]
	v_cvt_pk_bf16_f32 v179, v74, v75
	v_cvt_pk_bf16_f32 v178, v72, v73
	v_mov_b32_e32 v68, v2
	v_mfma_f32_16x16x32_bf16 v[80:83], v[84:87], v[92:95], 0
	v_mov_b32_e32 v69, v2
	v_mfma_f32_16x16x32_bf16 v[64:67], v[64:67], v[176:179], v[96:99]
	v_mfma_f32_16x16x32_bf16 v[60:63], v[60:63], v[176:179], v[100:103]
	s_nop 6
	v_cvt_pk_bf16_f32 v67, v66, v67
	v_cvt_pk_bf16_f32 v66, v64, v65
	s_nop 1
	v_mfma_f32_16x16x32_bf16 v[64:67], v[84:87], v[66:69], 0
	v_cvt_pk_bf16_f32 v85, v82, v83
	v_cvt_pk_bf16_f32 v84, v80, v81
	v_mov_b32_e32 v68, v70
	v_mov_b32_e32 v69, v71
	v_mov_b32_e32 v70, v2
	v_mov_b32_e32 v71, v2
	v_mfma_f32_16x16x32_bf16 v[76:79], v[0:3], v[84:87], v[76:79]
	s_nop 7
	v_cvt_pk_bf16_f32 v85, v78, v79
	v_cvt_pk_bf16_f32 v84, v76, v77
	s_nop 1
	v_mfma_f32_16x16x32_bf16 v[76:79], v[68:71], v[84:87], 0
	v_cvt_pk_bf16_f32 v85, v66, v67
	v_cvt_pk_bf16_f32 v84, v64, v65
	s_nop 1
	v_mfma_f32_16x16x32_bf16 v[60:63], v[0:3], v[84:87], v[60:63]
	v_cvt_pk_bf16_f32 v87, v30, v31
	v_cvt_pk_bf16_f32 v86, v28, v29
	v_cvt_pk_bf16_f32 v85, v34, v35
	v_cvt_pk_bf16_f32 v84, v32, v33
	s_nop 3
	v_cvt_pk_bf16_f32 v1, v62, v63
	v_cvt_pk_bf16_f32 v0, v60, v61
	s_nop 1
	v_mfma_f32_16x16x32_bf16 v[60:63], v[68:71], v[0:3], 0
	v_cvt_pk_bf16_f32 v0, v168, s0
	ds_write_b16 v156, v0 offset:53248
	v_cvt_pk_bf16_f32 v0, v169, s0
	ds_write_b16 v156, v0 offset:53776
	v_cvt_pk_bf16_f32 v0, v170, s0
	ds_write_b16 v156, v0 offset:54304
	v_cvt_pk_bf16_f32 v0, v171, s0
	ds_write_b16 v156, v0 offset:54832
	v_cvt_pk_bf16_f32 v0, v88, s0
	ds_write_b16 v156, v0 offset:61696
	v_cvt_pk_bf16_f32 v0, v89, s0
	ds_write_b16 v156, v0 offset:62224
	v_cvt_pk_bf16_f32 v0, v90, s0
	ds_write_b16 v156, v0 offset:62752
	v_cvt_pk_bf16_f32 v0, v91, s0
	ds_write_b16 v156, v0 offset:63280
	v_cvt_pk_bf16_f32 v0, v80, s0
	ds_write_b16 v157, v0
	v_cvt_pk_bf16_f32 v0, v81, s0
	ds_write_b16 v158, v0
	v_cvt_pk_bf16_f32 v0, v82, s0
	ds_write_b16 v159, v0
	v_cvt_pk_bf16_f32 v0, v83, s0
	ds_write_b16 v160, v0
	v_cvt_pk_bf16_f32 v0, v76, s0
	ds_write_b16 v161, v0
	v_cvt_pk_bf16_f32 v0, v77, s0
	ds_write_b16 v162, v0
	v_cvt_pk_bf16_f32 v0, v78, s0
	ds_write_b16 v163, v0
	v_cvt_pk_bf16_f32 v0, v79, s0
	ds_write_b16 v164, v0
	v_cvt_pk_bf16_f32 v0, v140, s0
	ds_write_b16 v156, v0 offset:53280
	v_cvt_pk_bf16_f32 v0, v141, s0
	ds_write_b16 v156, v0 offset:53808
	v_cvt_pk_bf16_f32 v0, v142, s0
	ds_write_b16 v156, v0 offset:54336
	v_cvt_pk_bf16_f32 v0, v143, s0
	ds_write_b16 v156, v0 offset:54864
	v_cvt_pk_bf16_f32 v0, v72, s0
	ds_write_b16 v156, v0 offset:61728
	v_cvt_pk_bf16_f32 v0, v73, s0
	ds_write_b16 v156, v0 offset:62256
	v_cvt_pk_bf16_f32 v0, v74, s0
	ds_write_b16 v156, v0 offset:62784
	v_cvt_pk_bf16_f32 v0, v75, s0
	ds_write_b16 v156, v0 offset:63312
	v_cvt_pk_bf16_f32 v0, v64, s0
	ds_write_b16 v180, v0
	v_cvt_pk_bf16_f32 v0, v65, s0
	ds_write_b16 v181, v0
	v_cvt_pk_bf16_f32 v0, v66, s0
	ds_write_b16 v182, v0
	v_cvt_pk_bf16_f32 v0, v67, s0
	ds_write_b16 v183, v0
	v_cvt_pk_bf16_f32 v0, v60, s0
	ds_write_b16 v184, v0
	v_cvt_pk_bf16_f32 v0, v61, s0
	ds_write_b16 v185, v0
	v_cvt_pk_bf16_f32 v0, v62, s0
	ds_write_b16 v186, v0
	v_cvt_pk_bf16_f32 v0, v63, s0
	v_mov_b32_e32 v3, v107
	v_mov_b32_e32 v88, v120
	v_mov_b32_e32 v89, v121
	ds_write_b16 v187, v0
	s_waitcnt lgkmcnt(0)
	s_barrier
	v_cvt_pk_bf16_f32 v63, v6, v7
	v_mul_lo_u32 v0, v88, s22
	v_lshlrev_b32_e32 v90, 3, v89
	v_add3_u32 v164, 16, v0, v90
	v_add_u32_e32 v0, 0xd000, v164
	ds_read_b64 v[72:73], v0 offset:256
	ds_read_b64 v[74:75], v0 offset:288
	ds_read_b64 v[76:77], v0 offset:320
	ds_read_b64 v[78:79], v0 offset:352
	v_cvt_pk_bf16_f32 v62, v4, v5
	v_cvt_pk_bf16_f32 v61, v10, v11
	v_cvt_pk_bf16_f32 v60, v8, v9
	ds_read_b64 v[80:81], v0 offset:384
	ds_read_b64 v[82:83], v0 offset:416
	v_cvt_pk_bf16_f32 v67, v14, v15
	s_waitcnt lgkmcnt(4)
	v_mfma_f32_16x16x32_bf16 v[72:75], v[72:75], v[60:63], 0
	v_cvt_pk_bf16_f32 v66, v12, v13
	v_cvt_pk_bf16_f32 v65, v18, v19
	v_cvt_pk_bf16_f32 v64, v16, v17
	ds_read_b64 v[92:93], v0 offset:448
	ds_read_b64 v[94:95], v0 offset:480
	v_mul_lo_u32 v0, v88, s21
	s_waitcnt lgkmcnt(4)
	v_mfma_f32_16x16x32_bf16 v[72:75], v[76:79], v[64:67], v[72:75]
	v_cvt_pk_bf16_f32 v71, v22, v23
	v_cvt_pk_bf16_f32 v70, v20, v21
	v_cvt_pk_bf16_f32 v69, v26, v27
	v_cvt_pk_bf16_f32 v68, v24, v25
	v_add3_u32 v165, s66, v90, v0
	ds_read_b64 v[76:77], v165
	ds_read_b64 v[78:79], v165 offset:32
	s_waitcnt lgkmcnt(4)
	v_mfma_f32_16x16x32_bf16 v[72:75], v[80:83], v[68:71], v[72:75]
	v_add_u32_e32 v1, 0xf000, v164
	ds_read_b64 v[98:99], v1 offset:640
	ds_read_b64 v[100:101], v1 offset:672
	v_add_u32_e32 v91, 0x1000, v165
	s_waitcnt lgkmcnt(4)
	v_mfma_f32_16x16x32_bf16 v[80:83], v[92:95], v[84:87], v[72:75]
	ds_read_b64 v[92:93], v165 offset:128
	ds_read_b64 v[94:95], v165 offset:160
	v_lshl_add_u32 v0, v88, 1, s61
	v_mad_u64_u32 v[102:103], s[12:13], v89, s25, v[0:1]
	ds_read_b64 v[72:73], v165 offset:64
	ds_read_b64 v[74:75], v165 offset:96
	s_waitcnt lgkmcnt(6)
	v_mfma_f32_16x16x32_bf16 v[76:79], v[76:79], v[60:63], 0
	s_waitcnt lgkmcnt(0)
	v_mfma_f32_16x16x32_bf16 v[72:75], v[72:75], v[64:67], v[76:79]
	s_nop 5
	ds_read_b64 v[76:77], v165 offset:192
	ds_read_b64 v[78:79], v165 offset:224
	v_mfma_f32_16x16x32_bf16 v[72:75], v[92:95], v[68:71], v[72:75]
	ds_read_b64 v[94:95], v1 offset:512
	ds_read_b64 v[96:97], v1 offset:544
	v_lshlrev_b32_e32 v92, 2, v89
	v_or_b32_e32 v176, 1, v92
	s_waitcnt lgkmcnt(2)
	v_mfma_f32_16x16x32_bf16 v[72:75], v[76:79], v[84:87], v[72:75]
	ds_read_b64 v[76:77], v1 offset:576
	ds_read_b64 v[78:79], v1 offset:608
	v_mad_u64_u32 v[160:161], s[12:13], v176, s22, v[0:1]
	s_waitcnt lgkmcnt(2)
	v_mfma_f32_16x16x32_bf16 v[94:97], v[94:97], v[60:63], 0
	v_add_u32_e32 v172, 0x1ef0, v160
	s_cselect_b32 s12, 16, 0
	s_add_u32 s12, s12, 0x1c8fc
	s_waitcnt lgkmcnt(0)
	v_mfma_f32_16x16x32_bf16 v[76:79], v[76:79], v[64:67], v[94:97]
	s_addc_u32 s13, s1, 0
	s_nop 1
	ds_read_b64 v[94:95], v91 offset:256
	ds_read_b64 v[96:97], v91 offset:288
	s_cmp_lg_u64 s[6:7], 0
	s_cselect_b32 s99, 0, -1
	s_cselect_b32 s101, 0, -1
	s_cselect_b32 s98, 1, -1
	s_lshl_b32 s98, s98, 12
	s_lshl_b32 s100, s98, 4
	s_cmp_lg_u64 s[12:13], 0
	v_mfma_f32_16x16x32_bf16 v[76:79], v[98:101], v[68:71], v[76:79]
	ds_read_b64 v[98:99], v1 offset:704
	ds_read_b64 v[100:101], v1 offset:736
	ds_read_u16 v0, v102 offset:53248
	ds_read_u16 v1, v160 offset:53248
	ds_read_u16 v93, v160 offset:53776
	ds_read_u16 v102, v160 offset:54304
	ds_read_u16 v161, v160 offset:61168
	ds_read_u16 v162, v160 offset:61696
	ds_read_u16 v166, v160 offset:62224
	ds_read_u16 v167, v160 offset:62752
	ds_read_b64 v[140:141], v91 offset:320
	ds_read_b64 v[142:143], v91 offset:352
	s_waitcnt lgkmcnt(8)
	v_lshlrev_b32_e32 v1, 16, v1
	v_mfma_f32_16x16x32_bf16 v[94:97], v[94:97], v[60:63], 0
	v_lshlrev_b32_e32 v0, 16, v0
	v_pk_add_f32 v[0:1], v[0:1], v[80:81] neg_lo:[0,1] neg_hi:[0,1]
	v_add_u32_e32 v80, 0x4200, v164
	v_mfma_f32_16x16x32_bf16 v[98:101], v[98:101], v[84:87], v[76:79]
	v_add_u32_e32 v168, 0xd000, v80
	s_waitcnt lgkmcnt(6)
	v_lshlrev_b32_e32 v81, 16, v102
	ds_read_b64 v[156:157], v91 offset:448
	ds_read_b64 v[158:159], v91 offset:480
	ds_read_b64 v[76:77], v91 offset:384
	ds_read_b64 v[78:79], v91 offset:416
	s_waitcnt lgkmcnt(4)
	v_mfma_f32_16x16x32_bf16 v[94:97], v[140:143], v[64:67], v[94:97]
	ds_read_b64 v[140:141], v168 offset:256
	ds_read_b64 v[142:143], v168 offset:288
	v_lshlrev_b32_e32 v80, 16, v93
	v_pk_add_f32 v[102:103], v[80:81], v[82:83] neg_lo:[0,1] neg_hi:[0,1]
	ds_read_b64 v[80:81], v168 offset:320
	ds_read_b64 v[82:83], v168 offset:352
	s_waitcnt lgkmcnt(4)
	v_mfma_f32_16x16x32_bf16 v[76:79], v[76:79], v[68:71], v[94:97]
	s_nop 2
	ds_read_b64 v[94:95], v168 offset:384
	ds_read_b64 v[96:97], v168 offset:416
	v_add_u32_e32 v93, 0x2000, v165
	v_lshlrev_b32_e32 v163, 16, v162
	s_waitcnt lgkmcnt(4)
	v_mfma_f32_16x16x32_bf16 v[140:143], v[140:143], v[60:63], 0
	v_lshlrev_b32_e32 v162, 16, v161
	v_add_u32_e32 v165, 0x3000, v165
	s_cselect_b32 s1, s12, -1
	v_mfma_f32_16x16x32_bf16 v[76:79], v[156:159], v[84:87], v[76:79]
	ds_read_b64 v[156:157], v168 offset:448
	ds_read_b64 v[158:159], v168 offset:480
	v_pk_add_f32 v[168:169], v[162:163], v[98:99] neg_lo:[0,1] neg_hi:[0,1]
	v_lshlrev_b32_e32 v99, 16, v167
	s_waitcnt lgkmcnt(4)
	v_mfma_f32_16x16x32_bf16 v[80:83], v[80:83], v[64:67], v[140:143]
	v_lshlrev_b32_e32 v98, 16, v166
	v_pk_add_f32 v[170:171], v[98:99], v[100:101] neg_lo:[0,1] neg_hi:[0,1]
	ds_read_b64 v[98:99], v93 offset:704
	ds_read_b64 v[100:101], v93 offset:736
	ds_read_b64 v[140:141], v93 offset:512
	ds_read_b64 v[142:143], v93 offset:544
	s_waitcnt lgkmcnt(6)
	v_mfma_f32_16x16x32_bf16 v[80:83], v[94:97], v[68:71], v[80:83]
	ds_read_b64 v[94:95], v93 offset:576
	ds_read_b64 v[96:97], v93 offset:608
	s_add_i32 s66, 16, 0x258fc
	s_and_b64 s[12:13], s[14:15], exec
	s_waitcnt lgkmcnt(6)
	v_mfma_f32_16x16x32_bf16 v[156:159], v[156:159], v[84:87], v[80:83]
	s_cselect_b32 s1, s1, s66
	s_nop 0
	ds_read_b64 v[80:81], v93 offset:640
	ds_read_b64 v[82:83], v93 offset:672
	s_waitcnt lgkmcnt(4)
	v_mfma_f32_16x16x32_bf16 v[140:143], v[140:143], v[60:63], 0
	v_add_u32_e32 v91, 16, v92
	s_waitcnt lgkmcnt(2)
	v_mfma_f32_16x16x32_bf16 v[94:97], v[94:97], v[64:67], v[140:143]
	v_add_u32_e32 v93, 32, v92
	s_waitcnt lgkmcnt(0)
	v_mfma_f32_16x16x32_bf16 v[80:83], v[80:83], v[68:71], v[94:97]
	s_nop 1
	v_add_u32_e32 v140, 0x3ff0, v160
	s_nop 1
	v_add_u32_e32 v94, 0x6300, v164
	v_add_u32_e32 v162, 0xd000, v94
	ds_read_b64 v[94:95], v162 offset:256
	ds_read_b64 v[96:97], v162 offset:288
	ds_read_u16 v160, v172 offset:61696
	ds_read_u16 v141, v172 offset:62224
	ds_read_u16 v164, v172 offset:62752
	ds_read_u16 v166, v172 offset:63280
	ds_read_u16 v183, v140 offset:61696
	ds_read_u16 v184, v140 offset:62224
	ds_read_u16 v185, v140 offset:62752
	ds_read_u16 v186, v140 offset:63280
	s_waitcnt lgkmcnt(6)
	v_lshlrev_b32_e32 v161, 16, v141
	ds_read_b64 v[140:141], v162 offset:320
	ds_read_b64 v[142:143], v162 offset:352
	v_mfma_f32_16x16x32_bf16 v[80:83], v[98:101], v[84:87], v[80:83]
	ds_read_b64 v[98:99], v162 offset:384
	ds_read_b64 v[100:101], v162 offset:416
	v_lshlrev_b32_e32 v160, 16, v160
	v_pk_add_f32 v[172:173], v[160:161], v[156:157] neg_lo:[0,1] neg_hi:[0,1]
	v_mfma_f32_16x16x32_bf16 v[94:97], v[94:97], v[60:63], 0
	ds_read_b64 v[160:161], v162 offset:448
	ds_read_b64 v[162:163], v162 offset:480
	s_waitcnt lgkmcnt(10)
	v_lshlrev_b32_e32 v157, 16, v166
	v_lshlrev_b32_e32 v156, 16, v164
	s_waitcnt lgkmcnt(4)
	v_mfma_f32_16x16x32_bf16 v[94:97], v[140:143], v[64:67], v[94:97]
	ds_read_b64 v[140:141], v165 offset:768
	ds_read_b64 v[142:143], v165 offset:800
	v_pk_add_f32 v[174:175], v[156:157], v[158:159] neg_lo:[0,1] neg_hi:[0,1]
	s_waitcnt lgkmcnt(4)
	v_mfma_f32_16x16x32_bf16 v[94:97], v[98:101], v[68:71], v[94:97]
	ds_read_b64 v[98:99], v165 offset:832
	ds_read_b64 v[100:101], v165 offset:864
	s_add_i32 s60, s60, 1
	v_cmp_lt_u32_e32 vcc, s60, v109
	s_waitcnt lgkmcnt(2)
	v_mfma_f32_16x16x32_bf16 v[60:63], v[140:143], v[60:63], 0
	v_mfma_f32_16x16x32_bf16 v[156:159], v[160:163], v[84:87], v[94:97]
	ds_read_b64 v[160:161], v165 offset:896
	ds_read_b64 v[162:163], v165 offset:928
	ds_read_b64 v[166:167], v165 offset:992
	ds_read_b64 v[164:165], v165 offset:960
	s_nop 0
	v_lshlrev_b32_e32 v97, 16, v184
	s_waitcnt lgkmcnt(4)
	v_mfma_f32_16x16x32_bf16 v[60:63], v[98:101], v[64:67], v[60:63]
	v_lshlrev_b32_e32 v65, 16, v186
	v_lshlrev_b32_e32 v64, 16, v185
	v_lshlrev_b32_e32 v96, 16, v183
	s_waitcnt lgkmcnt(2)
	v_mfma_f32_16x16x32_bf16 v[60:63], v[160:163], v[68:71], v[60:63]
	v_add_f32_e64 v64, v64, -v158
	v_add_f32_e64 v65, v65, -v159
	v_mul_lo_u32 v159, v88, s24
	v_pk_add_f32 v[96:97], v[96:97], v[156:157] neg_lo:[0,1] neg_hi:[0,1]
	s_waitcnt lgkmcnt(0)
	v_mfma_f32_16x16x32_bf16 v[68:71], v[164:167], v[84:87], v[60:63]
	v_cvt_pk_bf16_f32 v66, v96, v97
	v_cvt_pk_bf16_f32 v67, v64, v65
	v_cvt_pk_bf16_f32 v65, v174, v175
	v_cvt_pk_bf16_f32 v60, v0, v1
	v_mov_b32_e32 v0, s1
	s_add_i32 s1, 16, 0x19200
	v_add_u32_e32 v158, s1, v90
	v_add_u32_e32 v84, v158, v159
	ds_read_b64 v[96:97], v84
	ds_read_b64 v[98:99], v84 offset:32
	ds_read_b32 v0, v0
	v_cvt_pk_bf16_f32 v61, v102, v103
	ds_read_b64 v[100:101], v84 offset:64
	ds_read_b64 v[102:103], v84 offset:96
	v_cvt_pk_bf16_f32 v63, v170, v171
	v_cvt_pk_bf16_f32 v62, v168, v169
	s_waitcnt lgkmcnt(2)
	v_mul_f32_e32 v157, 0x3fb8aa3b, v0
	v_lshlrev_b32_e32 v0, 6, v155
	v_lshl_add_u32 v155, v89, 4, s65
	ds_read_b128 v[140:143], v155
	v_ashrrev_i32_e32 v89, 31, v88
	v_lshl_add_u64 v[84:85], v[88:89], 2, v[116:117]
	v_mfma_f32_16x16x32_bf16 v[86:89], v[96:99], v[60:63], 0
	v_cvt_pk_bf16_f32 v64, v172, v173
	ds_read_b128 v[96:99], v155 offset:64
	s_waitcnt lgkmcnt(1)
	v_mul_f32_e32 v140, 0x3fb8aa3b, v140
	v_exp_f32_e32 v140, v140
	v_mfma_f32_16x16x32_bf16 v[86:89], v[100:103], v[64:67], v[86:89]
	v_sub_u32_e32 v100, 63, v92
	v_ashrrev_i32_e32 v1, 31, v0
	v_cndmask_b32_e64 v100, v100, v92, s[6:7]
	v_lshl_add_u64 v[0:1], v[0:1], 0, v[104:105]
	v_ashrrev_i32_e32 v101, 31, v100
	s_nop 2
	v_fma_f32 v72, v72, v140, v86
	v_lshl_add_u64 v[100:101], v[0:1], 0, v[100:101]
	v_mul_f32_e32 v86, 0x3fb8aa3b, v141
	v_lshlrev_b64 v[100:101], 12, v[100:101]
	v_exp_f32_e32 v86, v86
	v_lshl_add_u64 v[194:195], v[84:85], 0, v[100:101]
	global_store_dword v[194:195], v72, off
	v_fma_f32 v86, v73, v86, v87
	v_lshl_add_u64 v[190:191], v[194:195], 0, s[98:99]
	v_mul_f32_e32 v87, 0x3fb8aa3b, v142
	global_store_dword v[190:191], v86, off
	v_exp_f32_e32 v87, v87
	s_nop 0
	v_fma_f32 v74, v74, v87, v88
	v_lshl_add_u64 v[192:193], v[190:191], 0, s[98:99]
	v_add_u32_e32 v140, 0x900, v159
	global_store_dword v[192:193], v74, off
	v_mul_f32_e32 v72, 0x3fb8aa3b, v143
	v_add_u32_e32 v73, v158, v140
	v_exp_f32_e32 v72, v72
	ds_read_b64 v[100:101], v73
	ds_read_b64 v[102:103], v73 offset:32
	v_fmac_f32_e32 v89, v75, v72
	ds_read_b64 v[74:75], v73 offset:96
	ds_read_b64 v[72:73], v73 offset:64
	s_waitcnt lgkmcnt(2)
	v_mfma_f32_16x16x32_bf16 v[100:103], v[100:103], v[60:63], 0
	v_lshl_add_u64 v[190:191], v[192:193], 0, s[98:99]
	global_store_dword v[190:191], v89, off
	v_mul_f32_e32 v86, 0x3fb8aa3b, v96
	v_exp_f32_e32 v87, v86
	s_waitcnt lgkmcnt(0)
	v_mfma_f32_16x16x32_bf16 v[72:75], v[72:75], v[64:67], v[100:103]
	v_add_u32_e32 v141, 0x1200, v159
	s_nop 0
	ds_read_b128 v[100:103], v155 offset:128
	v_add_u32_e32 v94, 48, v92
	s_nop 2
	s_nop 0
	v_fma_f32 v72, v76, v87, v72
	v_mul_f32_e32 v76, 0x3fb8aa3b, v97
	v_exp_f32_e32 v76, v76
	v_lshl_add_u64 v[194:195], v[194:195], 0, s[100:101]
	global_store_dword v[194:195], v72, off
	v_fma_f32 v76, v77, v76, v73
	v_lshl_add_u64 v[190:191], v[194:195], 0, s[98:99]
	v_mul_f32_e32 v77, 0x3fb8aa3b, v98
	global_store_dword v[190:191], v76, off
	v_exp_f32_e32 v77, v77
	s_nop 0
	v_fma_f32 v74, v78, v77, v74
	v_lshl_add_u64 v[192:193], v[190:191], 0, s[98:99]
	global_store_dword v[192:193], v74, off
	v_add_u32_e32 v74, v158, v141
	v_mul_f32_e32 v73, 0x3fb8aa3b, v99
	ds_read_b64 v[86:87], v74
	ds_read_b64 v[88:89], v74 offset:32
	v_exp_f32_e32 v73, v73
	ds_read_b64 v[96:97], v74 offset:64
	ds_read_b64 v[98:99], v74 offset:96
	v_fmac_f32_e32 v75, v79, v73
	v_lshl_add_u64 v[190:191], v[192:193], 0, s[98:99]
	global_store_dword v[190:191], v75, off
	s_waitcnt lgkmcnt(2)
	v_mfma_f32_16x16x32_bf16 v[72:75], v[86:89], v[60:63], 0
	ds_read_b128 v[76:79], v155 offset:192
	v_mul_f32_e32 v86, 0x3fb8aa3b, v100
	v_exp_f32_e32 v87, v86
	s_waitcnt lgkmcnt(1)
	v_mfma_f32_16x16x32_bf16 v[72:75], v[96:99], v[64:67], v[72:75]
	v_add_u32_e32 v100, 0x1b00, v159
	s_nop 2
	s_nop 1
	s_nop 1
	v_fma_f32 v72, v80, v87, v72
	v_mul_f32_e32 v80, 0x3fb8aa3b, v101
	v_exp_f32_e32 v80, v80
	v_lshl_add_u64 v[194:195], v[194:195], 0, s[100:101]
	global_store_dword v[194:195], v72, off
	v_fma_f32 v80, v81, v80, v73
	v_lshl_add_u64 v[190:191], v[194:195], 0, s[98:99]
	v_mul_f32_e32 v81, 0x3fb8aa3b, v102
	global_store_dword v[190:191], v80, off
	v_exp_f32_e32 v81, v81
	s_nop 0
	v_fma_f32 v74, v82, v81, v74
	v_lshl_add_u64 v[192:193], v[190:191], 0, s[98:99]
	global_store_dword v[192:193], v74, off
	v_mul_f32_e32 v72, 0x3fb8aa3b, v103
	v_add_u32_e32 v74, v158, v100
	v_exp_f32_e32 v73, v72
	ds_read_b64 v[86:87], v74
	ds_read_b64 v[88:89], v74 offset:32
	v_fmac_f32_e32 v75, v83, v73
	ds_read_b64 v[80:81], v74 offset:64
	ds_read_b64 v[82:83], v74 offset:96
	s_waitcnt lgkmcnt(2)
	v_mfma_f32_16x16x32_bf16 v[86:89], v[86:89], v[60:63], 0
	v_lshl_add_u64 v[190:191], v[192:193], 0, s[98:99]
	global_store_dword v[190:191], v75, off
	v_mul_f32_e32 v72, 0x3fb8aa3b, v76
	v_exp_f32_e32 v76, v72
	s_waitcnt lgkmcnt(0)
	v_mfma_f32_16x16x32_bf16 v[72:75], v[80:83], v[64:67], v[86:89]
	s_nop 2
	s_nop 4
	v_fma_f32 v68, v68, v76, v72
	v_mul_f32_e32 v72, 0x3fb8aa3b, v77
	v_exp_f32_e32 v72, v72
	v_lshl_add_u64 v[194:195], v[194:195], 0, s[100:101]
	global_store_dword v[194:195], v68, off
	v_fma_f32 v72, v69, v72, v73
	v_add_u32_e32 v101, s0, v159
	v_add_u32_e32 v73, v101, v90
	ds_read_b64 v[80:81], v73
	ds_read_b64 v[82:83], v73 offset:32
	v_lshl_add_u64 v[190:191], v[194:195], 0, s[98:99]
	global_store_dword v[190:191], v72, off
	v_mul_f32_e32 v69, 0x3fb8aa3b, v78
	v_exp_f32_e32 v68, v157
	v_exp_f32_e32 v69, v69
	v_xor_b32_e32 v77, 8, v91
	v_pk_mul_f32 v[8:9], v[8:9], v[68:69] op_sel_hi:[1,0]
	v_pk_mul_f32 v[10:11], v[10:11], v[68:69] op_sel_hi:[1,0]
	v_fma_f32 v69, v70, v69, v74
	v_add_u32_e32 v70, s0, v141
	s_waitcnt lgkmcnt(0)
	v_mfma_f32_16x16x32_bf16 v[8:11], v[80:83], v[60:63], v[8:11]
	ds_read_b64 v[80:81], v73 offset:64
	ds_read_b64 v[82:83], v73 offset:96
	v_add_u32_e32 v73, s0, v140
	v_xad_u32 v76, v90, 16, v73
	v_lshl_add_u32 v77, v77, 1, v73
	ds_read_b64 v[86:87], v76
	ds_read_b64 v[88:89], v77
	v_xor_b32_e32 v76, 8, v93
	v_lshl_add_u32 v76, v76, 1, v73
	v_xor_b32_e32 v77, 8, v94
	v_lshl_add_u32 v73, v77, 1, v73
	ds_read_b64 v[96:97], v76
	ds_read_b64 v[98:99], v73
	v_xad_u32 v74, v90, 32, v70
	v_xor_b32_e32 v76, 16, v91
	s_waitcnt lgkmcnt(4)
	v_mfma_f32_16x16x32_bf16 v[8:11], v[80:83], v[64:67], v[8:11]
	v_lshl_add_u32 v76, v76, 1, v70
	ds_read_b64 v[80:81], v74
	ds_read_b64 v[82:83], v76
	v_xor_b32_e32 v74, 16, v93
	v_xor_b32_e32 v76, 16, v94
	v_pk_mul_f32 v[4:5], v[4:5], v[68:69] op_sel_hi:[1,0]
	v_pk_mul_f32 v[6:7], v[6:7], v[68:69] op_sel_hi:[1,0]
	v_lshl_add_u32 v74, v74, 1, v70
	v_lshl_add_u32 v70, v76, 1, v70
	s_waitcnt lgkmcnt(4)
	v_mfma_f32_16x16x32_bf16 v[4:7], v[86:89], v[60:63], v[4:7]
	ds_read_b64 v[86:87], v74
	ds_read_b64 v[88:89], v70
	v_add_u32_e32 v70, s0, v100
	v_pk_mul_f32 v[16:17], v[16:17], v[68:69] op_sel_hi:[1,0]
	v_pk_mul_f32 v[18:19], v[18:19], v[68:69] op_sel_hi:[1,0]
	v_xad_u32 v74, v90, 48, v70
	v_xor_b32_e32 v76, 24, v91
	s_waitcnt lgkmcnt(2)
	v_mfma_f32_16x16x32_bf16 v[16:19], v[80:83], v[60:63], v[16:19]
	v_lshl_add_u32 v76, v76, 1, v70
	ds_read_b64 v[80:81], v74
	ds_read_b64 v[82:83], v76
	v_xor_b32_e32 v74, 24, v93
	v_lshl_add_u32 v74, v74, 1, v70
	v_xor_b32_e32 v76, 24, v94
	v_lshl_add_u64 v[192:193], v[190:191], 0, s[98:99]
	v_mfma_f32_16x16x32_bf16 v[4:7], v[96:99], v[64:67], v[4:7]
	v_lshl_add_u32 v70, v76, 1, v70
	ds_read_b64 v[96:97], v74
	ds_read_b64 v[98:99], v70
	global_store_dword v[192:193], v69, off
	v_xad_u32 v72, v90, 64, v101
	v_xor_b32_e32 v73, 32, v91
	v_mul_f32_e32 v70, 0x3fb8aa3b, v79
	v_lshl_add_u32 v73, v73, 1, v101
	ds_read_b64 v[76:77], v72 offset:9216
	ds_read_b64 v[78:79], v73 offset:9216
	v_pk_mul_f32 v[12:13], v[12:13], v[68:69] op_sel_hi:[1,0]
	v_pk_mul_f32 v[14:15], v[14:15], v[68:69] op_sel_hi:[1,0]
	v_xor_b32_e32 v72, 32, v93
	v_xor_b32_e32 v73, 32, v94
	v_exp_f32_e32 v70, v70
	s_waitcnt lgkmcnt(4)
	v_mfma_f32_16x16x32_bf16 v[12:15], v[80:83], v[60:63], v[12:15]
	v_lshl_add_u32 v72, v72, 1, v101
	v_lshl_add_u32 v73, v73, 1, v101
	s_movk_i32 s0, 0x50
	v_pk_mul_f32 v[24:25], v[24:25], v[68:69] op_sel_hi:[1,0]
	v_pk_mul_f32 v[26:27], v[26:27], v[68:69] op_sel_hi:[1,0]
	ds_read_b64 v[80:81], v72 offset:9216
	ds_read_b64 v[82:83], v73 offset:9216
	v_xad_u32 v72, v90, s0, v101
	v_xor_b32_e32 v73, 40, v91
	s_waitcnt lgkmcnt(2)
	v_mfma_f32_16x16x32_bf16 v[24:27], v[76:79], v[60:63], v[24:27]
	v_lshl_add_u32 v73, v73, 1, v101
	ds_read_b64 v[76:77], v72 offset:11520
	ds_read_b64 v[78:79], v73 offset:11520
	v_xor_b32_e32 v72, 40, v93
	v_lshl_add_u32 v72, v72, 1, v101
	v_xor_b32_e32 v73, 40, v94
	v_fmac_f32_e32 v75, v71, v70
	s_movk_i32 s0, 0x60
	v_xor_b32_e32 v70, 48, v91
	v_mfma_f32_16x16x32_bf16 v[16:19], v[86:89], v[64:67], v[16:19]
	v_lshl_add_u32 v73, v73, 1, v101
	ds_read_b64 v[86:87], v72 offset:11520
	ds_read_b64 v[88:89], v73 offset:11520
	v_pk_mul_f32 v[20:21], v[20:21], v[68:69] op_sel_hi:[1,0]
	v_mfma_f32_16x16x32_bf16 v[12:15], v[96:99], v[64:67], v[12:15]
	v_mul_f32_e64 v22, v22, v68
	v_mul_f32_e64 v23, v23, v68
	v_xad_u32 v69, v90, s0, v101
	v_lshl_add_u32 v72, v70, 1, v101
	ds_read_b64 v[70:71], v69 offset:13824
	ds_read_b64 v[72:73], v72 offset:13824
	v_pk_mul_f32 v[32:33], v[32:33], v[68:69] op_sel_hi:[1,0]
	v_pk_mul_f32 v[34:35], v[34:35], v[68:69] op_sel_hi:[1,0]
	v_xor_b32_e32 v69, 48, v93
	v_lshl_add_u32 v69, v69, 1, v101
	v_xor_b32_e32 v74, 48, v94
	s_waitcnt lgkmcnt(0)
	v_mfma_f32_16x16x32_bf16 v[32:35], v[70:73], v[60:63], v[32:35]
	s_movk_i32 s0, 0x70
	v_xor_b32_e32 v70, 56, v91
	v_lshl_add_u32 v74, v74, 1, v101
	v_mfma_f32_16x16x32_bf16 v[20:23], v[76:79], v[60:63], v[20:23]
	ds_read_b64 v[76:77], v69 offset:13824
	ds_read_b64 v[78:79], v74 offset:13824
	v_xad_u32 v69, v90, s0, v101
	v_lshl_add_u32 v72, v70, 1, v101
	ds_read_b64 v[70:71], v69 offset:16128
	ds_read_b64 v[72:73], v72 offset:16128
	v_xor_b32_e32 v69, 56, v93
	v_lshl_add_u32 v69, v69, 1, v101
	v_xor_b32_e32 v74, 56, v94
	v_mfma_f32_16x16x32_bf16 v[24:27], v[80:83], v[64:67], v[24:27]
	v_lshl_add_u32 v74, v74, 1, v101
	ds_read_b64 v[80:81], v69 offset:16128
	ds_read_b64 v[82:83], v74 offset:16128
	v_pk_mul_f32 v[28:29], v[28:29], v[68:69] op_sel_hi:[1,0]
	v_pk_mul_f32 v[30:31], v[30:31], v[68:69] op_sel_hi:[1,0]
	v_mfma_f32_16x16x32_bf16 v[20:23], v[86:89], v[64:67], v[20:23]
	v_lshl_add_u64 v[190:191], v[192:193], 0, s[98:99]
	s_waitcnt lgkmcnt(2)
	v_mfma_f32_16x16x32_bf16 v[28:31], v[70:73], v[60:63], v[28:31]
	global_store_dword v[190:191], v75, off
	v_mfma_f32_16x16x32_bf16 v[32:35], v[76:79], v[64:67], v[32:35]
	s_waitcnt lgkmcnt(0)
	v_mfma_f32_16x16x32_bf16 v[28:31], v[80:83], v[64:67], v[28:31]
	s_and_saveexec_b64 s[0:1], vcc
	s_cbranch_execz .LBB0_644
	v_and_b32_e32 v0, 7, v3
	v_ashrrev_i32_e32 v1, 3, v3
	v_cmp_eq_u32_e32 vcc, 0, v0
	s_and_saveexec_b64 s[12:13], vcc
	s_cbranch_execz .LBB0_643
	s_and_b64 s[66:67], s[14:15], exec
	s_cselect_b32 s66, s55, s64
	s_add_i32 s67, 16, 0x1c900
	s_add_i32 vcc_lo, 16, 0x25900
	s_and_b64 s[64:65], s[14:15], exec
	s_cselect_b32 s64, vcc_lo, s67
	v_lshlrev_b32_e32 v3, 2, v1
	v_add_u32_e32 v60, s64, v3
	v_add_u32_e32 v3, s66, v3
	s_waitcnt vmcnt(17)
	ds_write_b32 v3, v122
	ds_write_b32 v60, v110
	s_branch .LBB0_643
